# MLA attention items: per-XCD queues (XCD x takes batch x's 128 latent items + 8 context items) so each K/V set streams through one L2; guarded by the 8-XCD check
# baseline (speedup 1.0000x reference)
; #define DECODE2(it) int b, hd; size_t q0; int nT; \
;     if ((it) < NL2) { b = (it) >> 6; hd = ((it) >> 4) & 3; q0 = (size_t)b * SEQA + CTXL + ((it) & 15) * 256; nT = 68; } \
;     else { int j_ = (it) - NL2; b = j_ >> 2; hd = j_ & 3; q0 = (size_t)b * SEQA; nT = 4; }
; #define DECODE_ITEM(it) int b, hd, qb; bool isctx; \
;     if ((it) < NL) { b = (it) >> 7; hd = ((it) >> 5) & 3; qb = (it) & 31; isctx = false; } \
;     else { int j_ = (it) - NL; b = j_ >> 3; hd = (j_ >> 1) & 3; qb = j_ & 1; isctx = true; } \
;     const size_t q0 = (size_t)b * SEQA + (isctx ? 0 : CTXL) + qb * 128; const int nT = isctx ? 4 : 68;
; DI int fetch_item(unsigned* ctr, char* smem) {
;   volatile int* slot = (volatile int*)(smem + SMEM_BYTES - 16);
;   __syncthreads();
;   if (threadIdx.x == 0) *slot = (int)__hip_atomic_fetch_add(ctr, 1u, __ATOMIC_RELAXED, __HIP_MEMORY_SCOPE_AGENT);
;   __syncthreads();
;   return *slot;
; }
; DI void phase_mix(const Params& p, int l, char* smem, int tid) {
;     ...
;   for (int it = fetch_item(q, smem); it < NT2; it = fetch_item(q, smem)) {
;     DECODE2(it)
;     const int hk = hd >> 1;
;     attn_item2<64>(p.QD + q0 * 256 + hd * 64, 256, p.KD + ((size_t)b * 2 + hk) * SEQA * 64, 64, p.VtAD + ((size_t)b * 384 + 256 + hk * 64) * SEQA, nT,
;                    p.G + q0 * 1024 + 768 + hd * 64, p.Pk + q0 * PKW + 768 + 768 + hd * 64, smem, tid);
;   }
;     ...
;   for (int it = fetch_item(q + 64, smem); it < NL + NC; it = fetch_item(q + 64, smem)) {
;     DECODE_ITEM(it)
;     attn_item<96, false>(p.QB + q0 * 384 + hd * 96, 384, p.KB + ((size_t)b * 4 + hd) * SEQA * 96, 96, p.VtB + ((size_t)b * 4 + hd) * 64 * SEQA, nT, 1.f,
;                          0, 0, 0, nullptr, p.G + q0 * 1024 + 256 + hd * 64, p.Pk + q0 * PKW + 768 + 256 + hd * 64, smem, tid);
.LBB0_881:
	s_or_b64 exec, exec, s[0:1]
	v_lshlrev_b32_e32 v14, 2, v206
	ds_read_b32 v208, v14 offset:36864
	ds_read_b32 v209, v14 offset:37888
	ds_read_b32 v210, v14 offset:38912
	ds_read_b32 v211, v14 offset:39936
	ds_read_b32 v212, v14 offset:40960
	ds_read_b32 v213, v14 offset:41984
	ds_read_b32 v214, v14 offset:43008
	ds_read_b32 v215, v14 offset:44032
	ds_read_b32 v216, v14 offset:45056
	ds_read_b32 v217, v14 offset:46080
	ds_read_b32 v218, v14 offset:47104
	ds_read_b32 v219, v14 offset:48128
	ds_read_b32 v220, v14 offset:49152
	ds_read_b32 v221, v14 offset:50176
	ds_read_b32 v222, v14 offset:51200
	ds_read_b32 v223, v14 offset:52224
	s_waitcnt lgkmcnt(0)
	s_barrier
	s_and_saveexec_b64 s[0:1], s[92:93]
	s_movk_i32 s11, 0x400
	s_movk_i32 s8, 0xd0
	s_mov_b32 s16, 0xf149f2ca
	s_cbranch_execz .LBB0_885
	s_mov_b64 s[4:5], exec
	v_mbcnt_lo_u32_b32 v0, s4, 0
	v_mbcnt_hi_u32_b32 v0, s5, v0
	v_cmp_eq_u32_e32 vcc, 0, v0
	s_and_saveexec_b64 s[2:3], vcc
	s_cbranch_execz .LBB0_884
	s_bcnt1_i32_b64 s4, s[4:5]
	v_mov_b32_e32 v2, s4
	v_mov_b32_e32 v182, 0x12604
	ds_read_b32 v182, v182
	s_waitcnt lgkmcnt(0)
	v_readfirstlane_b32 s4, v182
	s_cmp_eq_u32 s4, 8
	s_cbranch_scc1 .Lbx_a0
	v_readlane_b32 s4, v254, 51
	v_readlane_b32 s5, v254, 52
	s_nop 4
	global_atomic_add v2, v1, v2, s[4:5] offset:256 sc0
	s_branch .Lbx_a0d
.Lbx_a0:
	v_readlane_b32 s5, v254, 19
	s_getreg_b32 s4, hwreg(HW_REG_XCC_ID, 0, 4)
	s_lshl_b32 s4, s4, 6
	s_lshl_b32 s5, s5, 9
	s_add_u32 s4, s4, s5
	s_add_u32 s4, s4, 0x1da5c600
	s_add_u32 s4, s96, s4
	s_addc_u32 s5, s97, 0
	global_atomic_add v2, v1, v2, s[4:5] sc0
.Lbx_a0d:
.LBB0_884:
	s_or_b64 exec, exec, s[2:3]
	s_waitcnt vmcnt(0)
	v_readfirstlane_b32 s2, v2
	s_nop 1
	v_add_u32_e32 v0, s2, v0
	flat_store_dword v[154:155], v0 sc0 sc1
	s_waitcnt vmcnt(0)
.LBB0_885:
	s_or_b64 exec, exec, s[0:1]
	s_waitcnt lgkmcnt(0)
	s_barrier
	flat_load_dword v0, v[154:155] sc0 sc1
	s_waitcnt vmcnt(0)
	v_readlane_b32 s0, v254, 17
	v_readlane_b32 s1, v254, 18
	s_and_b64 s[0:1], s[0:1], exec
	s_cselect_b32 s0, 64, 0
	s_or_b32 s10, s0, 0x400
	v_writelane_b32 v254, s0, 53
	s_waitcnt lgkmcnt(0)
	v_mov_b32_e32 v182, 0x12604
	ds_read_b32 v182, v182
	s_waitcnt lgkmcnt(0)
	v_readfirstlane_b32 s2, v182
	s_cmp_eq_u32 s2, 8
	s_cbranch_scc0 .Lbx_r0
	s_getreg_b32 s2, hwreg(HW_REG_XCC_ID, 0, 4)
	s_lshl_b32 s3, s2, 7
	v_add_u32_e32 v182, s3, v0
	s_lshl_b32 s3, s2, 3
	s_addk_i32 s3, 0x380
	v_add_u32_e32 v183, s3, v0
	s_sub_u32 s3, s10, 0x400
	s_lshr_b32 s3, s3, 3
	s_addk_i32 s3, 0x80
	v_mov_b32_e32 v186, 0x7fffffff
	v_cmp_gt_u32_e32 vcc, s3, v0
	v_cndmask_b32_e32 v183, v186, v183, vcc
	v_cmp_gt_u32_e32 vcc, 0x80, v0
	v_cndmask_b32_e32 v0, v183, v182, vcc
.Lbx_r0:
	v_cmp_gt_i32_e32 vcc, s10, v0
	s_and_saveexec_b64 s[0:1], vcc
	s_cbranch_execz .LBB0_902
	v_ashrrev_i32_e32 v2, 1, v156
	s_movk_i32 s2, 0xffe0
	v_bfi_b32 v2, s2, v2, v156
	v_mad_i64_i32 v[112:113], s[2:3], v2, s24, 0
	s_mov_b32 s2, 0x2aaaaaab
	s_nop 0
	v_mul_hi_i32 v6, v156, s2
	v_lshrrev_b32_e32 v8, 31, v6
	v_ashrrev_i32_e32 v6, 1, v6
	v_add_u32_e32 v9, v6, v8
	v_mul_lo_u32 v6, v9, 12
	v_sub_u32_e32 v8, v156, v6
	v_add_u32_e32 v6, 0x100, v156
	v_mul_hi_i32 v10, v6, s2
	v_lshrrev_b32_e32 v11, 31, v10
	v_ashrrev_i32_e32 v10, 1, v10
	v_add_u32_e32 v10, v10, v11
	v_mul_lo_u32 v11, v10, 12
	v_sub_u32_e32 v11, v6, v11
	v_add_u32_e32 v6, 0x200, v156
	v_mul_hi_i32 v12, v6, s2
	v_lshrrev_b32_e32 v13, 31, v12
	v_ashrrev_i32_e32 v12, 1, v12
	v_ashrrev_i32_e32 v14, 3, v156
	v_add_u32_e32 v12, v12, v13
	v_add_u32_e32 v15, 32, v14
	v_mad_i64_i32 v[120:121], s[2:3], v9, s45, 0
	v_mad_i64_i32 v[122:123], s[2:3], v10, s45, 0
	v_mad_i64_i32 v[124:125], s[2:3], v12, s45, 0
	v_mad_i64_i32 v[126:127], s[2:3], v14, s23, 0
	v_mad_i64_i32 v[128:129], s[2:3], v15, s23, 0
	v_ashrrev_i32_e32 v3, 31, v2
	v_lshlrev_b32_e32 v114, 3, v8
	v_mul_lo_u32 v13, v12, 12
	s_movk_i32 s2, 0x88
	v_sub_u32_e32 v13, v6, v13
	v_ashrrev_i32_e32 v115, 31, v114
	v_mul_lo_u32 v170, v14, s2
	v_mad_i64_i32 v[130:131], s[2:3], v2, s33, 0
	v_lshlrev_b64 v[132:133], 11, v[2:3]
	v_and_b32_e32 v2, 7, v156
	v_lshlrev_b32_e32 v118, 3, v13
	v_lshl_or_b32 v134, v2, 4, v126
	v_lshlrev_b64 v[2:3], 1, v[114:115]
	v_bfe_u32 v7, v156, 5, 1
	v_lshlrev_b32_e32 v116, 3, v11
	v_ashrrev_i32_e32 v119, 31, v118
	v_mul_lo_u32 v153, v10, s8
	v_mad_i64_i32 v[2:3], s[2:3], v9, s45, v[2:3]
	s_mov_b64 s[4:5], 0x12323000
	v_and_b32_e32 v5, 31, v156
	v_ashrrev_i32_e32 v117, 31, v116
	v_mul_lo_u32 v149, v9, s8
	v_lshl_add_u32 v157, v11, 4, v153
	v_lshlrev_b32_e32 v11, 4, v7
	v_lshl_add_u64 v[136:137], v[2:3], 0, s[4:5]
	v_lshlrev_b64 v[2:3], 1, v[118:119]
	v_lshlrev_b32_e32 v4, 3, v7
	v_lshlrev_b32_e32 v6, 3, v156
	v_lshl_add_u32 v151, v8, 4, v149
	v_mul_u32_u24_e32 v8, 0xd0, v5
	v_mad_u32_u24 v172, v5, s8, v11
	v_mul_i32_i24_e32 v5, 0xffffffb8, v5
	v_mad_i64_i32 v[138:139], s[2:3], v12, s45, v[2:3]
	v_lshlrev_b64 v[2:3], 1, v[116:117]
	v_and_b32_e32 v6, 56, v6
	v_mul_lo_u32 v168, v12, s8
	v_add3_u32 v173, v8, v5, v4
	v_lshlrev_b32_e32 v8, 2, v7
	v_mad_i64_i32 v[2:3], s[2:3], v10, s45, v[2:3]
	v_lshl_add_u32 v169, v13, 4, v168
	v_lshl_add_u32 v171, v6, 1, v170
	v_mov_b32_e32 v135, v127
	v_lshl_add_u64 v[140:141], v[2:3], 0, s[4:5]
	s_mov_b64 s[4:5], 0
	v_lshlrev_b32_e32 v142, 1, v4
	v_lshlrev_b32_e32 v174, 1, v114
	v_lshlrev_b32_e32 v175, 1, v116
	v_lshlrev_b32_e32 v176, 1, v118
	v_lshlrev_b32_e32 v144, 1, v6
	v_lshlrev_b32_e32 v146, 1, v8
	s_branch .LBB0_889

; DI int fetch_item(unsigned* ctr, char* smem) {
;   volatile int* slot = (volatile int*)(smem + SMEM_BYTES - 16);
;   __syncthreads();
;   if (threadIdx.x == 0) *slot = (int)__hip_atomic_fetch_add(ctr, 1u, __ATOMIC_RELAXED, __HIP_MEMORY_SCOPE_AGENT);
;   __syncthreads();
;   return *slot;
; }
; DI void phase_mix(const Params& p, int l, char* smem, int tid) {
;     ...
;   for (int it = fetch_item(q + 64, smem); it < NL + NC; it = fetch_item(q + 64, smem)) {
.LBB0_888:
	s_or_b64 exec, exec, s[6:7]
	s_waitcnt lgkmcnt(0)
	s_barrier
	flat_load_dword v0, v[154:155] sc0 sc1
	s_waitcnt vmcnt(0) lgkmcnt(0)
	v_mov_b32_e32 v182, 0x12604
	ds_read_b32 v182, v182
	s_waitcnt lgkmcnt(0)
	v_readfirstlane_b32 s2, v182
	s_cmp_eq_u32 s2, 8
	s_cbranch_scc0 .Lbx_r1
	s_getreg_b32 s2, hwreg(HW_REG_XCC_ID, 0, 4)
	s_lshl_b32 s3, s2, 7
	v_add_u32_e32 v182, s3, v0
	s_lshl_b32 s3, s2, 3
	s_addk_i32 s3, 0x380
	v_add_u32_e32 v183, s3, v0
	s_sub_u32 s3, s10, 0x400
	s_lshr_b32 s3, s3, 3
	s_addk_i32 s3, 0x80
	v_mov_b32_e32 v186, 0x7fffffff
	v_cmp_gt_u32_e32 vcc, s3, v0
	v_cndmask_b32_e32 v183, v186, v183, vcc
	v_cmp_gt_u32_e32 vcc, 0x80, v0
	v_cndmask_b32_e32 v0, v183, v182, vcc
.Lbx_r1:
	v_cmp_le_i32_e32 vcc, s10, v0
	s_or_b64 s[4:5], vcc, s[4:5]
	s_andn2_b64 exec, exec, s[4:5]
	s_cbranch_execz .LBB0_902

; #define MFMA(a, b, c) __builtin_amdgcn_mfma_f32_32x32x16_bf16((a), (b), (c), 0, 0, 0)
; DI unsigned pack2(float a, float b) { f32v2 v = {a, b}; return __builtin_bit_cast(unsigned, __builtin_convertvector(v, bf16v2)); }
; DI float xhalf_sum(float v) { auto r = __builtin_amdgcn_permlane32_swap(__float_as_uint(v), __float_as_uint(v), false, false); return __uint_as_float(r[0]) + __uint_as_float(r[1]); }
; #define LSTORE(bf) { *(uint4*)&Ks[bf][kr0][kc0] = rk0; *(uint4*)&Ks[bf][kr1][kc1] = rk1; if (NKC == 3) *(uint4*)&Ks[bf][kr2][kc2] = rk2; \
;     *(uint2*)&Vs[bf][vd0][vk0] = make_uint2(rv0.x, rv0.y); *(uint2*)&Vs[bf][vd0][vk0 + 4] = make_uint2(rv0.z, rv0.w); \
;     *(uint2*)&Vs[bf][vd0 + 32][vk0] = make_uint2(rv1.x, rv1.y); *(uint2*)&Vs[bf][vd0 + 32][vk0 + 4] = make_uint2(rv1.z, rv1.w); }
; template <int DK, bool NA> ...
;     ...
;       float ls = 0.f;
; #pragma unroll
;       for (int kb = 0; kb < 2; kb++)
; #pragma unroll
;         for (int i = 0; i < 16; i++) { float pv = __builtin_amdgcn_exp2f(s[kb][i] - mn); s[kb][i] = pv; ls += pv; }
;       l_run += ls;
;       bf16x8 pf[2][2];
; #pragma unroll
;       for (int kb = 0; kb < 2; kb++)
; #pragma unroll
;         for (int sx = 0; sx < 2; sx++) {
;           uint4 u; u.x = pack2(s[kb][8 * sx], s[kb][8 * sx + 1]); u.y = pack2(s[kb][8 * sx + 2], s[kb][8 * sx + 3]);
;           u.z = pack2(s[kb][8 * sx + 4], s[kb][8 * sx + 5]); u.w = pack2(s[kb][8 * sx + 6], s[kb][8 * sx + 7]);
;           pf[kb][sx] = __builtin_bit_cast(bf16x8, u);
;         }
; #pragma unroll
;       for (int db = 0; db < 2; db++)
; #pragma unroll
;         for (int kb = 0; kb < 2; kb++)
; #pragma unroll
;           for (int sx = 0; sx < 2; sx++) {
;             const u16* vp = &Vs[buf][db * 32 + r][32 * kb + 16 * sx + 4 * h];
;             uint2 lo = *(const uint2*)vp, hi = *(const uint2*)(vp + 8);
;             uint4 u; u.x = lo.x; u.y = lo.y; u.z = hi.x; u.w = hi.y;
;             o[db] = MFMA(__builtin_bit_cast(bf16x8, u), pf[kb][sx], o[db]);
;           }
;     }
;     if (t + 1 < nTiles) LSTORE(buf ^ 1);
;     __syncthreads();
;   }
;     ...
;   const float lt = xhalf_sum(l_run);
;   const float inv = __builtin_amdgcn_rcpf(lt);
.LBB0_899:
	v_sub_f32_e32 v2, v64, v145
	v_exp_f32_e32 v64, v2
	v_sub_f32_e32 v2, v65, v145
	v_exp_f32_e32 v65, v2
	v_sub_f32_e32 v2, v66, v145
	v_exp_f32_e32 v66, v2
	v_sub_f32_e32 v2, v67, v145
	v_exp_f32_e32 v67, v2
	v_sub_f32_e32 v2, v68, v145
	v_exp_f32_e32 v68, v2
	v_sub_f32_e32 v2, v69, v145
	v_exp_f32_e32 v69, v2
	v_sub_f32_e32 v2, v70, v145
	v_exp_f32_e32 v70, v2
	v_sub_f32_e32 v2, v71, v145
	v_exp_f32_e32 v71, v2
	v_sub_f32_e32 v2, v72, v145
	v_exp_f32_e32 v72, v2
	v_sub_f32_e32 v2, v73, v145
	v_exp_f32_e32 v73, v2
	v_sub_f32_e32 v2, v74, v145
	v_exp_f32_e32 v74, v2
	v_sub_f32_e32 v2, v75, v145
	v_exp_f32_e32 v75, v2
	v_sub_f32_e32 v2, v76, v145
	v_exp_f32_e32 v76, v2
	v_sub_f32_e32 v2, v77, v145
	v_exp_f32_e32 v77, v2
	v_sub_f32_e32 v2, v78, v145
	v_exp_f32_e32 v78, v2
	v_sub_f32_e32 v2, v79, v145
	v_exp_f32_e32 v79, v2
	v_sub_f32_e32 v2, v48, v145
	v_exp_f32_e32 v80, v2
	v_sub_f32_e32 v2, v49, v145
	v_exp_f32_e32 v81, v2
	v_sub_f32_e32 v2, v50, v145
	v_exp_f32_e32 v82, v2
	v_sub_f32_e32 v2, v51, v145
	v_exp_f32_e32 v83, v2
	v_sub_f32_e32 v2, v52, v145
	v_exp_f32_e32 v84, v2
	v_sub_f32_e32 v2, v53, v145
	v_exp_f32_e32 v85, v2
	v_sub_f32_e32 v2, v54, v145
	v_exp_f32_e32 v86, v2
	v_sub_f32_e32 v2, v55, v145
	v_exp_f32_e32 v87, v2
	v_sub_f32_e32 v2, v56, v145
	v_exp_f32_e32 v56, v2
	v_sub_f32_e32 v2, v57, v145
	v_mad_u32_u24 v0, v0, s23, v173
	v_exp_f32_e32 v57, v2
	v_sub_f32_e32 v2, v58, v145
	v_add_u32_e32 v14, 0x6800, v0
	v_exp_f32_e32 v58, v2
	ds_read2_b64 v[2:5], v14 offset1:2
	v_sub_f32_e32 v6, v59, v145
	v_exp_f32_e32 v59, v6
	v_cvt_pk_bf16_f32 v6, v64, v65
	v_cvt_pk_bf16_f32 v7, v66, v67
	v_cvt_pk_bf16_f32 v8, v68, v69
	v_cvt_pk_bf16_f32 v9, v70, v71
	ds_read2_b64 v[10:13], v14 offset0:4 offset1:6
	ds_read2_b64 v[48:51], v14 offset0:8 offset1:10
	s_waitcnt lgkmcnt(2)
	v_mfma_f32_32x32x16_bf16 v[32:47], v[2:5], v[6:9], v[32:47]
	v_cvt_pk_bf16_f32 v2, v72, v73
	v_cvt_pk_bf16_f32 v3, v74, v75
	v_cvt_pk_bf16_f32 v4, v76, v77
	v_cvt_pk_bf16_f32 v5, v78, v79
	ds_read2_b64 v[52:55], v14 offset0:12 offset1:14
	v_sub_f32_e32 v15, v60, v145
	v_exp_f32_e32 v60, v15
	s_waitcnt lgkmcnt(2)
	v_mfma_f32_32x32x16_bf16 v[32:47], v[10:13], v[2:5], v[32:47]
	v_cvt_pk_bf16_f32 v10, v80, v81
	v_cvt_pk_bf16_f32 v11, v82, v83
	v_cvt_pk_bf16_f32 v12, v84, v85
	v_cvt_pk_bf16_f32 v13, v86, v87
	v_sub_f32_e32 v15, v61, v145
	v_exp_f32_e32 v61, v15
	v_sub_f32_e32 v15, v62, v145
	s_waitcnt lgkmcnt(1)
	v_mfma_f32_32x32x16_bf16 v[32:47], v[48:51], v[10:13], v[32:47]
	v_sub_f32_e32 v14, v63, v145
	v_exp_f32_e32 v62, v15
	v_exp_f32_e32 v63, v14
	v_cvt_pk_bf16_f32 v48, v56, v57
	v_cvt_pk_bf16_f32 v49, v58, v59
	v_cvt_pk_bf16_f32 v50, v60, v61
	v_cvt_pk_bf16_f32 v51, v62, v63
	v_add_u32_e32 v88, 0x7800, v0
	v_mov_b64_e32 v[14:15], s[90:91]
	s_waitcnt lgkmcnt(0)
	v_mfma_f32_32x32x16_bf16 v[32:47], v[52:55], v[48:51], v[32:47]
	ds_read2_b64 v[52:55], v88 offset0:32 offset1:34
	v_mad_u64_u32 v[14:15], s[2:3], v158, s33, v[14:15]
	v_mov_b32_e32 v0, v15
	s_waitcnt lgkmcnt(0)
	v_mfma_f32_32x32x16_bf16 v[16:31], v[52:55], v[6:9], v[16:31]
	ds_read2_b64 v[6:9], v88 offset0:36 offset1:38
	v_mad_u64_u32 v[52:53], s[2:3], v159, s33, v[0:1]
	v_mov_b32_e32 v15, v52
	v_lshlrev_b32_e32 v0, 7, v147
	v_lshl_add_u64 v[14:15], v[14:15], 0, v[0:1]
	v_mov_b32_e32 v147, v1
	s_waitcnt lgkmcnt(0)
	v_mfma_f32_32x32x16_bf16 v[16:31], v[6:9], v[2:5], v[16:31]
	v_lshl_add_u64 v[2:3], v[14:15], 0, v[130:131]
	v_lshl_add_u64 v[2:3], v[2:3], 0, v[146:147]
	ds_read2_b64 v[4:7], v88 offset0:40 offset1:42
	ds_read2_b64 v[52:55], v88 offset0:44 offset1:46
	s_waitcnt lgkmcnt(0)
	s_barrier
	global_load_dwordx2 v[8:9], v[2:3], off offset:2048
	v_mfma_f32_32x32x16_bf16 v[16:31], v[4:7], v[10:13], v[16:31]
	global_load_dwordx2 v[6:7], v[2:3], off offset:2064
	global_load_dwordx2 v[10:11], v[2:3], off offset:2080
	v_readlane_b32 s2, v253, 48
	v_lshlrev_b64 v[4:5], 11, v[158:159]
	v_readlane_b32 s3, v253, 49
	s_nop 1
	v_lshl_add_u64 v[4:5], s[2:3], 0, v[4:5]
	v_lshl_add_u64 v[4:5], v[4:5], 0, v[0:1]
	v_add_f32_e32 v0, 0, v64
	v_add_f32_e32 v0, v65, v0
	v_add_f32_e32 v0, v66, v0
	v_add_f32_e32 v0, v67, v0
	v_add_f32_e32 v0, v68, v0
	v_add_f32_e32 v0, v69, v0
	v_add_f32_e32 v0, v70, v0
	v_add_f32_e32 v0, v71, v0
	v_add_f32_e32 v0, v72, v0
	v_add_f32_e32 v0, v73, v0
	v_add_f32_e32 v0, v74, v0
	v_add_f32_e32 v0, v75, v0
	v_add_f32_e32 v0, v76, v0
	v_add_f32_e32 v0, v77, v0
	v_add_f32_e32 v0, v78, v0
	v_add_f32_e32 v0, v79, v0
	v_add_f32_e32 v0, v80, v0
	v_add_f32_e32 v0, v81, v0
	v_add_f32_e32 v0, v82, v0
	v_add_f32_e32 v0, v83, v0
	v_add_f32_e32 v0, v84, v0
	v_add_f32_e32 v0, v85, v0
	v_add_f32_e32 v0, v86, v0
	v_add_f32_e32 v0, v87, v0
	v_add_f32_e32 v0, v56, v0
	v_add_f32_e32 v0, v57, v0
	v_add_f32_e32 v0, v58, v0
	v_add_f32_e32 v0, v59, v0
	v_add_f32_e32 v0, v60, v0
	v_add_f32_e32 v0, v61, v0
	v_add_f32_e32 v0, v62, v0
	v_add_f32_e32 v0, v63, v0
	v_add_f32_e32 v0, v143, v0
	v_mov_b32_e32 v12, v0
	s_nop 1
	v_permlane32_swap_b32_e32 v0, v12
	v_add_f32_e32 v0, v0, v12
	global_load_dwordx2 v[12:13], v[2:3], off offset:2096
	v_mfma_f32_32x32x16_bf16 v[16:31], v[52:55], v[48:51], v[16:31]
	v_rcp_f32_e32 v0, v0
	v_lshl_add_u64 v[4:5], v[4:5], 0, v[132:133]
	v_lshl_add_u64 v[4:5], v[4:5], 0, v[146:147]
	v_pk_mul_f32 v[32:33], v[32:33], v[0:1] op_sel_hi:[1,0]
	s_waitcnt vmcnt(3)
; DI unsigned pack2(float a, float b) { f32v2 v = {a, b}; return __builtin_bit_cast(unsigned, __builtin_convertvector(v, bf16v2)); }
; DI float bflo(unsigned v) { return __uint_as_float(v << 16); }
; DI float bfhi(unsigned v) { return __uint_as_float(v & 0xffff0000u); }
; DI float silu(float x) { return x * sigm(x); }
; DI float xhalf_sum(float v) { auto r = __builtin_amdgcn_permlane32_swap(__float_as_uint(v), __float_as_uint(v), false, false); return __uint_as_float(r[0]) + __uint_as_float(r[1]); }
; template <int DK, bool NA> ...
;     ...
;   const float lt = xhalf_sum(l_run);
;   const float inv = __builtin_amdgcn_rcpf(lt);
;   const int q = w * 32 + r;
; #pragma unroll
;   for (int db = 0; db < 2; db++)
; #pragma unroll
;     for (int g = 0; g < 4; g++) {
;       const int d0 = 32 * db + 8 * g + 4 * h;
;       uint2 zz = *(const uint2*)(Zp + (size_t)q * PKW + d0);
;       uint2 ov; ov.x = pack2(o[db][4 * g] * inv * silu(bflo(zz.x)), o[db][4 * g + 1] * inv * silu(bfhi(zz.x)));
;       ov.y = pack2(o[db][4 * g + 2] * inv * silu(bflo(zz.y)), o[db][4 * g + 3] * inv * silu(bfhi(zz.y)));
;       *(uint2*)(Gp + (size_t)q * 1024 + d0) = ov;
;     }
	v_lshlrev_b32_e32 v14, 16, v8
	v_mul_f32_e32 v15, 0xbfb8aa3b, v14
	v_exp_f32_e32 v48, v15
	v_and_b32_e32 v15, 0xffff0000, v8
	v_mul_f32_e32 v8, 0xbfb8aa3b, v15
	v_exp_f32_e32 v8, v8
	v_add_f32_e32 v48, 1.0, v48
	v_rcp_f32_e32 v48, v48
	v_add_f32_e32 v8, 1.0, v8
	v_rcp_f32_e32 v49, v8
	v_lshlrev_b32_e32 v8, 16, v9
	v_and_b32_e32 v9, 0xffff0000, v9
	v_mul_f32_e32 v50, 0xbfb8aa3b, v8
	v_mul_f32_e32 v51, 0xbfb8aa3b, v9
	v_exp_f32_e32 v50, v50
	v_exp_f32_e32 v51, v51
	v_pk_mul_f32 v[14:15], v[48:49], v[14:15]
	v_add_f32_e32 v48, 1.0, v50
	v_add_f32_e32 v49, 1.0, v51
	v_rcp_f32_e32 v48, v48
	v_rcp_f32_e32 v49, v49
	v_pk_mul_f32 v[14:15], v[32:33], v[14:15]
	v_pk_mul_f32 v[32:33], v[34:35], v[0:1] op_sel_hi:[1,0]
	v_cvt_pk_bf16_f32 v14, v14, v15
	v_pk_mul_f32 v[8:9], v[48:49], v[8:9]
	global_load_dwordx2 v[34:35], v[2:3], off offset:2112
	v_pk_mul_f32 v[8:9], v[32:33], v[8:9]
	v_pk_mul_f32 v[32:33], v[36:37], v[0:1] op_sel_hi:[1,0]
	v_cvt_pk_bf16_f32 v15, v8, v9
	s_waitcnt vmcnt(3)
	v_lshlrev_b32_e32 v8, 16, v6
	v_mul_f32_e32 v9, 0xbfb8aa3b, v8
	global_store_dwordx2 v[4:5], v[14:15], off offset:512
	v_exp_f32_e32 v14, v9
	v_and_b32_e32 v9, 0xffff0000, v6
	v_mul_f32_e32 v6, 0xbfb8aa3b, v9
	v_exp_f32_e32 v6, v6
	v_add_f32_e32 v14, 1.0, v14
	v_rcp_f32_e32 v14, v14
	v_add_f32_e32 v6, 1.0, v6
	v_rcp_f32_e32 v15, v6
	v_lshlrev_b32_e32 v6, 16, v7
	v_and_b32_e32 v7, 0xffff0000, v7
	v_mul_f32_e32 v36, 0xbfb8aa3b, v6
	v_mul_f32_e32 v37, 0xbfb8aa3b, v7
	v_exp_f32_e32 v36, v36
	v_exp_f32_e32 v37, v37
	v_pk_mul_f32 v[8:9], v[14:15], v[8:9]
	v_add_f32_e32 v14, 1.0, v36
	v_add_f32_e32 v15, 1.0, v37
	v_rcp_f32_e32 v14, v14
	v_rcp_f32_e32 v15, v15
	v_pk_mul_f32 v[8:9], v[32:33], v[8:9]
	v_pk_mul_f32 v[32:33], v[38:39], v[0:1] op_sel_hi:[1,0]
	v_cvt_pk_bf16_f32 v8, v8, v9
	v_pk_mul_f32 v[6:7], v[14:15], v[6:7]
	v_pk_mul_f32 v[14:15], v[40:41], v[0:1] op_sel_hi:[1,0]
	v_pk_mul_f32 v[6:7], v[32:33], v[6:7]
	global_load_dwordx2 v[32:33], v[2:3], off offset:2128
	v_cvt_pk_bf16_f32 v9, v6, v7
	s_waitcnt vmcnt(4)
	v_lshlrev_b32_e32 v6, 16, v10
	v_mul_f32_e32 v7, 0xbfb8aa3b, v6
	global_store_dwordx2 v[4:5], v[8:9], off offset:528
	v_exp_f32_e32 v8, v7
	v_and_b32_e32 v7, 0xffff0000, v10
	v_mul_f32_e32 v9, 0xbfb8aa3b, v7
	v_exp_f32_e32 v9, v9
	v_lshlrev_b32_e32 v10, 16, v11
	v_and_b32_e32 v11, 0xffff0000, v11
	v_add_f32_e32 v8, 1.0, v8
	v_add_f32_e32 v9, 1.0, v9
	v_mul_f32_e32 v36, 0xbfb8aa3b, v10
	v_mul_f32_e32 v37, 0xbfb8aa3b, v11
	v_rcp_f32_e32 v8, v8
	v_rcp_f32_e32 v9, v9
	v_exp_f32_e32 v36, v36
	v_exp_f32_e32 v37, v37
	v_pk_mul_f32 v[6:7], v[8:9], v[6:7]
	v_add_f32_e32 v8, 1.0, v36
	v_add_f32_e32 v9, 1.0, v37
	v_rcp_f32_e32 v8, v8
	v_rcp_f32_e32 v9, v9
	v_pk_mul_f32 v[6:7], v[14:15], v[6:7]
	v_pk_mul_f32 v[14:15], v[42:43], v[0:1] op_sel_hi:[1,0]
	v_cvt_pk_bf16_f32 v6, v6, v7
	v_pk_mul_f32 v[8:9], v[8:9], v[10:11]
	s_waitcnt vmcnt(4)
	v_lshlrev_b32_e32 v10, 16, v12
	v_mul_f32_e32 v7, 0xbfb8aa3b, v10
	v_pk_mul_f32 v[8:9], v[14:15], v[8:9]
	v_exp_f32_e32 v14, v7
	v_cvt_pk_bf16_f32 v7, v8, v9
	global_store_dwordx2 v[4:5], v[6:7], off offset:544
	v_and_b32_e32 v11, 0xffff0000, v12
	v_add_f32_e32 v6, 1.0, v14
	global_load_dwordx2 v[14:15], v[2:3], off offset:2144
	v_mul_f32_e32 v7, 0xbfb8aa3b, v11
	v_exp_f32_e32 v7, v7
	global_load_dwordx2 v[2:3], v[2:3], off offset:2160
	v_lshlrev_b32_e32 v12, 16, v13
	v_and_b32_e32 v13, 0xffff0000, v13
	v_add_f32_e32 v7, 1.0, v7
	v_mul_f32_e32 v36, 0xbfb8aa3b, v12
	v_mul_f32_e32 v37, 0xbfb8aa3b, v13
	v_rcp_f32_e32 v6, v6
	v_rcp_f32_e32 v7, v7
	v_exp_f32_e32 v36, v36
	v_exp_f32_e32 v37, v37
	v_pk_mul_f32 v[8:9], v[44:45], v[0:1] op_sel_hi:[1,0]
	v_pk_mul_f32 v[6:7], v[6:7], v[10:11]
	v_add_f32_e32 v10, 1.0, v36
	v_add_f32_e32 v11, 1.0, v37
	v_rcp_f32_e32 v10, v10
	v_rcp_f32_e32 v11, v11
	v_pk_mul_f32 v[6:7], v[8:9], v[6:7]
	v_pk_mul_f32 v[8:9], v[46:47], v[0:1] op_sel_hi:[1,0]
	v_cvt_pk_bf16_f32 v6, v6, v7
	v_pk_mul_f32 v[10:11], v[10:11], v[12:13]
	s_waitcnt vmcnt(6)
	v_lshlrev_b32_e32 v12, 16, v35
	v_pk_mul_f32 v[8:9], v[8:9], v[10:11]
	v_and_b32_e32 v13, 0xffff0000, v35
	v_cvt_pk_bf16_f32 v7, v8, v9
	global_store_dwordx2 v[4:5], v[6:7], off offset:560
	v_lshlrev_b32_e32 v6, 16, v34
	v_mul_f32_e32 v7, 0xbfb8aa3b, v6
	v_exp_f32_e32 v8, v7
	v_and_b32_e32 v7, 0xffff0000, v34
	v_mul_f32_e32 v9, 0xbfb8aa3b, v7
	v_exp_f32_e32 v9, v9
	v_add_f32_e32 v8, 1.0, v8
	v_pk_mul_f32 v[10:11], v[16:17], v[0:1] op_sel_hi:[1,0]
	v_mul_f32_e32 v16, 0xbfb8aa3b, v12
	v_add_f32_e32 v9, 1.0, v9
	v_mul_f32_e32 v17, 0xbfb8aa3b, v13
	v_rcp_f32_e32 v8, v8
	v_rcp_f32_e32 v9, v9
	v_exp_f32_e32 v16, v16
	v_exp_f32_e32 v17, v17
	v_pk_mul_f32 v[6:7], v[8:9], v[6:7]
	v_add_f32_e32 v8, 1.0, v16
	v_add_f32_e32 v9, 1.0, v17
	v_rcp_f32_e32 v8, v8
	v_rcp_f32_e32 v9, v9
	v_pk_mul_f32 v[6:7], v[10:11], v[6:7]
	v_pk_mul_f32 v[10:11], v[18:19], v[0:1] op_sel_hi:[1,0]
	v_cvt_pk_bf16_f32 v6, v6, v7
	v_pk_mul_f32 v[8:9], v[8:9], v[12:13]
	s_waitcnt vmcnt(5)
; DI unsigned pack2(float a, float b) { f32v2 v = {a, b}; return __builtin_bit_cast(unsigned, __builtin_convertvector(v, bf16v2)); }
; DI float bflo(unsigned v) { return __uint_as_float(v << 16); }
; DI float bfhi(unsigned v) { return __uint_as_float(v & 0xffff0000u); }
; DI float silu(float x) { return x * sigm(x); }
; template <int DK, bool NA> ...
;     ...
;       const int d0 = 32 * db + 8 * g + 4 * h;
;       uint2 zz = *(const uint2*)(Zp + (size_t)q * PKW + d0);
;       uint2 ov; ov.x = pack2(o[db][4 * g] * inv * silu(bflo(zz.x)), o[db][4 * g + 1] * inv * silu(bfhi(zz.x)));
;       ov.y = pack2(o[db][4 * g + 2] * inv * silu(bflo(zz.y)), o[db][4 * g + 3] * inv * silu(bfhi(zz.y)));
;       *(uint2*)(Gp + (size_t)q * 1024 + d0) = ov;
;     }
; DI int fetch_item(unsigned* ctr, char* smem) {
;   volatile int* slot = (volatile int*)(smem + SMEM_BYTES - 16);
;   __syncthreads();
;   if (threadIdx.x == 0) *slot = (int)__hip_atomic_fetch_add(ctr, 1u, __ATOMIC_RELAXED, __HIP_MEMORY_SCOPE_AGENT);
;   __syncthreads();
;   return *slot;
; }
	v_lshlrev_b32_e32 v12, 16, v33
	v_pk_mul_f32 v[8:9], v[10:11], v[8:9]
	v_and_b32_e32 v13, 0xffff0000, v33
	v_cvt_pk_bf16_f32 v7, v8, v9
	global_store_dwordx2 v[4:5], v[6:7], off offset:576
	v_lshlrev_b32_e32 v6, 16, v32
	v_mul_f32_e32 v7, 0xbfb8aa3b, v6
	v_exp_f32_e32 v8, v7
	v_and_b32_e32 v7, 0xffff0000, v32
	v_mul_f32_e32 v9, 0xbfb8aa3b, v7
	v_exp_f32_e32 v9, v9
	v_add_f32_e32 v8, 1.0, v8
	v_mul_f32_e32 v16, 0xbfb8aa3b, v12
	v_mul_f32_e32 v17, 0xbfb8aa3b, v13
	v_add_f32_e32 v9, 1.0, v9
	v_rcp_f32_e32 v8, v8
	v_rcp_f32_e32 v9, v9
	v_exp_f32_e32 v16, v16
	v_exp_f32_e32 v17, v17
	v_pk_mul_f32 v[10:11], v[20:21], v[0:1] op_sel_hi:[1,0]
	v_pk_mul_f32 v[6:7], v[8:9], v[6:7]
	v_add_f32_e32 v8, 1.0, v16
	v_add_f32_e32 v9, 1.0, v17
	v_rcp_f32_e32 v8, v8
	v_rcp_f32_e32 v9, v9
	v_pk_mul_f32 v[6:7], v[10:11], v[6:7]
	v_pk_mul_f32 v[10:11], v[22:23], v[0:1] op_sel_hi:[1,0]
	v_cvt_pk_bf16_f32 v6, v6, v7
	v_pk_mul_f32 v[8:9], v[8:9], v[12:13]
	s_waitcnt vmcnt(3)
	v_lshlrev_b32_e32 v12, 16, v15
	v_pk_mul_f32 v[8:9], v[10:11], v[8:9]
	v_and_b32_e32 v13, 0xffff0000, v15
	v_cvt_pk_bf16_f32 v7, v8, v9
	global_store_dwordx2 v[4:5], v[6:7], off offset:592
	v_lshlrev_b32_e32 v6, 16, v14
	v_mul_f32_e32 v7, 0xbfb8aa3b, v6
	v_exp_f32_e32 v8, v7
	v_and_b32_e32 v7, 0xffff0000, v14
	v_mul_f32_e32 v9, 0xbfb8aa3b, v7
	v_exp_f32_e32 v9, v9
	v_add_f32_e32 v8, 1.0, v8
	v_mul_f32_e32 v14, 0xbfb8aa3b, v12
	v_mul_f32_e32 v15, 0xbfb8aa3b, v13
	v_add_f32_e32 v9, 1.0, v9
	v_rcp_f32_e32 v8, v8
	v_rcp_f32_e32 v9, v9
	v_exp_f32_e32 v14, v14
	v_exp_f32_e32 v15, v15
	v_pk_mul_f32 v[10:11], v[24:25], v[0:1] op_sel_hi:[1,0]
	v_pk_mul_f32 v[6:7], v[8:9], v[6:7]
	v_add_f32_e32 v8, 1.0, v14
	v_add_f32_e32 v9, 1.0, v15
	v_rcp_f32_e32 v8, v8
	v_rcp_f32_e32 v9, v9
	v_pk_mul_f32 v[6:7], v[10:11], v[6:7]
	v_pk_mul_f32 v[10:11], v[26:27], v[0:1] op_sel_hi:[1,0]
	v_cvt_pk_bf16_f32 v6, v6, v7
	v_pk_mul_f32 v[8:9], v[8:9], v[12:13]
	s_nop 0
	v_pk_mul_f32 v[8:9], v[10:11], v[8:9]
	v_pk_mul_f32 v[10:11], v[28:29], v[0:1] op_sel_hi:[1,0]
	v_cvt_pk_bf16_f32 v7, v8, v9
	global_store_dwordx2 v[4:5], v[6:7], off offset:608
	s_waitcnt vmcnt(4)
	v_lshlrev_b32_e32 v6, 16, v2
	v_mul_f32_e32 v7, 0xbfb8aa3b, v6
	v_exp_f32_e32 v8, v7
	v_and_b32_e32 v7, 0xffff0000, v2
	v_mul_f32_e32 v2, 0xbfb8aa3b, v7
	v_exp_f32_e32 v2, v2
	v_add_f32_e32 v8, 1.0, v8
	v_rcp_f32_e32 v8, v8
	v_add_f32_e32 v2, 1.0, v2
	v_rcp_f32_e32 v9, v2
	v_lshlrev_b32_e32 v2, 16, v3
	v_and_b32_e32 v3, 0xffff0000, v3
	v_mul_f32_e32 v12, 0xbfb8aa3b, v2
	v_mul_f32_e32 v13, 0xbfb8aa3b, v3
	v_exp_f32_e32 v12, v12
	v_exp_f32_e32 v13, v13
	v_pk_mul_f32 v[6:7], v[8:9], v[6:7]
	v_add_f32_e32 v8, 1.0, v12
	v_add_f32_e32 v9, 1.0, v13
	v_rcp_f32_e32 v8, v8
	v_rcp_f32_e32 v9, v9
	v_pk_mul_f32 v[6:7], v[10:11], v[6:7]
	v_pk_mul_f32 v[10:11], v[30:31], v[0:1] op_sel_hi:[1,0]
	v_cvt_pk_bf16_f32 v6, v6, v7
	v_pk_mul_f32 v[2:3], v[8:9], v[2:3]
	s_nop 0
	v_pk_mul_f32 v[2:3], v[10:11], v[2:3]
	s_nop 0
	v_cvt_pk_bf16_f32 v7, v2, v3
	global_store_dwordx2 v[4:5], v[6:7], off offset:624
	s_barrier
	s_and_saveexec_b64 s[6:7], s[92:93]
	s_cbranch_execz .LBB0_888
	s_mov_b64 s[8:9], exec
	v_mbcnt_lo_u32_b32 v0, s8, 0
	v_mbcnt_hi_u32_b32 v0, s9, v0
	v_cmp_eq_u32_e32 vcc, 0, v0
	s_and_saveexec_b64 s[2:3], vcc
	s_cbranch_execz .LBB0_887
	s_bcnt1_i32_b64 s8, s[8:9]
	v_mov_b32_e32 v2, s8
	v_mov_b32_e32 v182, 0x12604
	ds_read_b32 v182, v182
	s_waitcnt lgkmcnt(0)
	v_readfirstlane_b32 s8, v182
	s_cmp_eq_u32 s8, 8
	s_cbranch_scc1 .Lbx_a1
	v_readlane_b32 s8, v254, 51
	v_readlane_b32 s9, v254, 52
	s_nop 4
	global_atomic_add v2, v1, v2, s[8:9] offset:256 sc0
	s_branch .Lbx_a1d
.Lbx_a1:
	v_readlane_b32 s9, v254, 19
	s_getreg_b32 s8, hwreg(HW_REG_XCC_ID, 0, 4)
	s_lshl_b32 s8, s8, 6
	s_lshl_b32 s9, s9, 9
	s_add_u32 s8, s8, s9
	s_add_u32 s8, s8, 0x1da5c600
	s_add_u32 s8, s96, s8
	s_addc_u32 s9, s97, 0
	global_atomic_add v2, v1, v2, s[8:9] sc0
.Lbx_a1d:
	s_branch .LBB0_887
.LBB0_902:
	s_or_b64 exec, exec, s[0:1]
	s_barrier
	s_and_saveexec_b64 s[0:1], s[92:93]
	s_cbranch_execz .LBB0_906
	s_mov_b64 s[4:5], exec
	v_mbcnt_lo_u32_b32 v0, s4, 0
	v_mbcnt_hi_u32_b32 v0, s5, v0
	v_cmp_eq_u32_e32 vcc, 0, v0
	s_and_saveexec_b64 s[2:3], vcc
	s_cbranch_execz .LBB0_905
	s_bcnt1_i32_b64 s4, s[4:5]
	v_mov_b32_e32 v2, s4
	v_readlane_b32 s4, v254, 51
	v_readlane_b32 s5, v254, 52
	s_nop 4
	global_atomic_add v2, v1, v2, s[4:5] offset:512 sc0
